# MLA attention softmax: score-minus-max with packed adds (negated broadcast max) and the 32-term row sum as a packed tree instead of a serial add chain
# speedup vs baseline: 1.0045x; 1.0010x over previous
; __global__ void __launch_bounds__(NTHR, 2) mega(P p) {
;     ...
;       if (!split0 || vb < 256)
;         for (int cid = vb; cid < 256; cid += (split0 ? 256 : nvb)) gdn_chain(p, cid, smem);
;       __syncthreads();
;       if (!split0 || vb >= 256) {
.LBB0_1106:
	s_setprio 0
	s_branch .LBB0_1108
	v_readlane_b32 s0, v220, 45
	v_readlane_b32 s1, v220, 46
	s_andn2_b64 vcc, exec, s[0:1]
	v_readlane_b32 s40, v218, 17
	s_waitcnt vmcnt(63) expcnt(7) lgkmcnt(15)
	s_barrier
	s_cbranch_vccz .LBB0_1112

; template <int DQK, bool SWA> ...
;     ...
;     float mx = -INFINITY;
; #pragma unroll
;     for (int mt = 0; mt < 2; ++mt)
; #pragma unroll
;       for (int i = 0; i < 16; ++i) mx = fmaxf(mx, s[mt][i]);
;     mx = fmaxf(mx, __shfl_xor(mx, 32));
;     const float mnew = fmaxf(m, mx);
;     const float alpha = __builtin_amdgcn_exp2f(m - mnew);
;     m = mnew;
;     float psum = 0.f;
; #pragma unroll
;     for (int mt = 0; mt < 2; ++mt)
; #pragma unroll
;       for (int i = 0; i < 16; ++i) {
;         const float pv = __builtin_amdgcn_exp2f(s[mt][i] - mnew);
;         s[mt][i] = pv;
;         psum += pv;
;       }
;     lsum = lsum * alpha + psum;
; #pragma unroll
;     for (int a = 0; a < 2; ++a)
; #pragma unroll
.LBB0_1184:
	s_and_b32 s18, s17, 1
	s_mul_i32 s19, s18, 0x3400
	v_add3_u32 v171, v160, s19, v163
	ds_read_b128 v[224:227], v171
	ds_read_b128 v[228:231], v171 offset:32
	ds_read_b128 v[232:235], v171 offset:64
	ds_read_b128 v[236:239], v171 offset:96
	ds_read_b128 v[240:243], v171 offset:128
	ds_read_b128 v[244:247], v171 offset:160
	ds_read_b128 v[248:251], v171 offset:6656
	ds_read_b128 v[252:255], v171 offset:6688
	s_mul_i32 s19, s18, 0x2400
	v_add3_u32 v184, v162, s19, v164
	v_add_u32_e32 v185, 0x6800, v184
	v_add_u32_e32 v184, 0x7800, v184
	s_andn2_b64 vcc, exec, s[0:1]
	s_waitcnt lgkmcnt(7)
	v_mfma_f32_32x32x16_bf16 v[48:63], v[224:227], v[64:67], 0
	ds_read_b128 v[224:227], v171 offset:6720
	s_waitcnt lgkmcnt(7)
	v_mfma_f32_32x32x16_bf16 v[48:63], v[228:231], v[68:71], v[48:63]
	ds_read_b128 v[228:231], v171 offset:6752
	s_waitcnt lgkmcnt(7)
	v_mfma_f32_32x32x16_bf16 v[48:63], v[232:235], v[72:75], v[48:63]
	ds_read_b128 v[232:235], v171 offset:6784
	s_waitcnt lgkmcnt(7)
	v_mfma_f32_32x32x16_bf16 v[48:63], v[236:239], v[76:79], v[48:63]
	ds_read_b128 v[236:239], v171 offset:6816
	s_waitcnt lgkmcnt(7)
	v_mfma_f32_32x32x16_bf16 v[48:63], v[240:243], v[80:83], v[48:63]
	s_waitcnt lgkmcnt(6)
	v_mfma_f32_32x32x16_bf16 v[48:63], v[244:247], v[84:87], v[48:63]
	s_waitcnt lgkmcnt(5)
	v_mfma_f32_32x32x16_bf16 v[32:47], v[248:251], v[64:67], 0
	s_waitcnt lgkmcnt(4)
	v_mfma_f32_32x32x16_bf16 v[32:47], v[252:255], v[68:71], v[32:47]
	s_waitcnt lgkmcnt(3)
	v_mfma_f32_32x32x16_bf16 v[32:47], v[224:227], v[72:75], v[32:47]
	v_max3_f32 v171, v48, s22, v49
	v_max3_f32 v171, v171, v50, v51
	s_waitcnt lgkmcnt(2)
	v_mfma_f32_32x32x16_bf16 v[32:47], v[228:231], v[76:79], v[32:47]
	v_max3_f32 v171, v171, v52, v53
	v_max3_f32 v171, v171, v54, v55
	s_waitcnt lgkmcnt(1)
	v_mfma_f32_32x32x16_bf16 v[32:47], v[232:235], v[80:83], v[32:47]
	v_max3_f32 v171, v171, v56, v57
	v_max3_f32 v171, v171, v58, v59
	s_waitcnt lgkmcnt(0)
	v_mfma_f32_32x32x16_bf16 v[32:47], v[236:239], v[84:87], v[32:47]
	v_max3_f32 v171, v171, v60, v61
	v_max3_f32 v171, v171, v62, v63
	ds_read2_b64 v[176:179], v185 offset1:2
	ds_read2_b64 v[180:183], v185 offset0:4 offset1:6
	s_nop 7
	v_max3_f32 v171, v171, v32, v33
	v_max3_f32 v171, v171, v34, v35
	v_max3_f32 v171, v171, v36, v37
	v_max3_f32 v171, v171, v38, v39
	v_max3_f32 v171, v171, v40, v41
	v_max3_f32 v171, v171, v42, v43
	v_max3_f32 v171, v171, v44, v45
	v_max3_f32 v171, v171, v46, v47
	v_mov_b32_e32 v172, v171
	s_nop 1
	v_permlane32_swap_b32 v172, v171
	s_waitcnt lgkmcnt(0)
	v_max3_f32 v171, v130, v171, v172
	v_sub_f32_e32 v130, v130, v171
	v_pk_add_f32 v[48:49], v[48:49], v[170:171] op_sel:[0,1] op_sel_hi:[1,1] neg_lo:[0,1] neg_hi:[0,1]
	v_pk_add_f32 v[50:51], v[50:51], v[170:171] op_sel:[0,1] op_sel_hi:[1,1] neg_lo:[0,1] neg_hi:[0,1]
	v_pk_add_f32 v[52:53], v[52:53], v[170:171] op_sel:[0,1] op_sel_hi:[1,1] neg_lo:[0,1] neg_hi:[0,1]
	v_pk_add_f32 v[54:55], v[54:55], v[170:171] op_sel:[0,1] op_sel_hi:[1,1] neg_lo:[0,1] neg_hi:[0,1]
	v_exp_f32_e32 v130, v130
	v_exp_f32_e32 v48, v48
	v_exp_f32_e32 v49, v49
	v_exp_f32_e32 v50, v50
	v_exp_f32_e32 v51, v51
	v_exp_f32_e32 v52, v52
	v_exp_f32_e32 v53, v53
	v_exp_f32_e32 v54, v54
	v_exp_f32_e32 v55, v55
	v_pk_mul_f32 v[30:31], v[30:31], v[130:131] op_sel_hi:[1,0]
	v_pk_mul_f32 v[28:29], v[28:29], v[130:131] op_sel_hi:[1,0]
	v_pk_mul_f32 v[26:27], v[26:27], v[130:131] op_sel_hi:[1,0]
	v_pk_mul_f32 v[24:25], v[24:25], v[130:131] op_sel_hi:[1,0]
	v_pk_mul_f32 v[22:23], v[22:23], v[130:131] op_sel_hi:[1,0]
	v_pk_mul_f32 v[20:21], v[20:21], v[130:131] op_sel_hi:[1,0]
	v_pk_mul_f32 v[18:19], v[18:19], v[130:131] op_sel_hi:[1,0]
	v_pk_mul_f32 v[16:17], v[16:17], v[130:131] op_sel_hi:[1,0]
	v_cvt_pk_bf16_f32 v172, v48, v49
	v_cvt_pk_bf16_f32 v173, v50, v51
	v_cvt_pk_bf16_f32 v174, v52, v53
	v_cvt_pk_bf16_f32 v175, v54, v55
	v_pk_mul_f32 v[14:15], v[14:15], v[130:131] op_sel_hi:[1,0]
	v_pk_mul_f32 v[12:13], v[12:13], v[130:131] op_sel_hi:[1,0]
	v_mfma_f32_32x32x16_bf16 v[16:31], v[176:179], v[172:175], v[16:31]
	ds_read2_b64 v[176:179], v184 offset0:64 offset1:66
	v_mul_f32_e64 v10, v10, v130
	v_mul_f32_e64 v11, v11, v130
	v_mul_f32_e64 v8, v8, v130
	v_mul_f32_e64 v9, v9, v130
	v_pk_mul_f32 v[6:7], v[6:7], v[130:131] op_sel_hi:[1,0]
	v_pk_mul_f32 v[4:5], v[4:5], v[130:131] op_sel_hi:[1,0]
	v_pk_mul_f32 v[2:3], v[2:3], v[130:131] op_sel_hi:[1,0]
	v_pk_mul_f32 v[0:1], v[0:1], v[130:131] op_sel_hi:[1,0]
	v_pk_add_f32 v[56:57], v[56:57], v[170:171] op_sel:[0,1] op_sel_hi:[1,1] neg_lo:[0,1] neg_hi:[0,1]
	s_waitcnt lgkmcnt(0)
; #define MFMA(a, b, c) __builtin_amdgcn_mfma_f32_32x32x16_bf16((a), (b), (c), 0, 0, 0)
; template <int DQK, bool SWA> ...
;     ...
; #pragma unroll
;     for (int mt = 0; mt < 2; ++mt)
; #pragma unroll
;       for (int i = 0; i < 16; ++i) {
;         const float pv = __builtin_amdgcn_exp2f(s[mt][i] - mnew);
;         s[mt][i] = pv;
;         psum += pv;
;       }
;     lsum = lsum * alpha + psum;
; #pragma unroll
;     for (int a = 0; a < 2; ++a)
; #pragma unroll
;       for (int i = 0; i < 16; ++i) o[a][i] *= alpha;
; #pragma unroll
;     for (int mt = 0; mt < 2; ++mt)
; #pragma unroll
;       for (int sx = 0; sx < 2; ++sx) {
;         uint4 pu;
;         pu.x = pack2(s[mt][8 * sx + 0], s[mt][8 * sx + 1]);
;         pu.y = pack2(s[mt][8 * sx + 2], s[mt][8 * sx + 3]);
;         pu.z = pack2(s[mt][8 * sx + 4], s[mt][8 * sx + 5]);
;         pu.w = pack2(s[mt][8 * sx + 6], s[mt][8 * sx + 7]);
;         const bf16x8 pfv = __builtin_bit_cast(bf16x8, pu);
; #pragma unroll
;         for (int dt = 0; dt < 2; ++dt) {
;           const u16* vp = Vt + buf * 64 * VSTR + (dt * 32 + r) * VSTR + mt * 32 + 16 * sx + 4 * hh;
;           const uint2 v0 = *(const uint2*)(vp);
;           const uint2 v1 = *(const uint2*)(vp + 8);
;           const uint4 vu = make_uint4(v0.x, v0.y, v1.x, v1.y);
;           o[dt] = MFMA(__builtin_bit_cast(bf16x8, vu), pfv, o[dt]);
;         }
;       }
;     if (it + 1 < nt) A_STORES(buf ^ 1);
;     __syncthreads();
	v_mfma_f32_32x32x16_bf16 v[0:15], v[176:179], v[172:175], v[0:15]
	ds_read2_b64 v[176:179], v184 offset0:68 offset1:70
	v_pk_add_f32 v[58:59], v[58:59], v[170:171] op_sel:[0,1] op_sel_hi:[1,1] neg_lo:[0,1] neg_hi:[0,1]
	v_pk_add_f32 v[60:61], v[60:61], v[170:171] op_sel:[0,1] op_sel_hi:[1,1] neg_lo:[0,1] neg_hi:[0,1]
	v_pk_add_f32 v[62:63], v[62:63], v[170:171] op_sel:[0,1] op_sel_hi:[1,1] neg_lo:[0,1] neg_hi:[0,1]
	v_exp_f32_e32 v56, v56
	v_exp_f32_e32 v57, v57
	v_exp_f32_e32 v58, v58
	v_exp_f32_e32 v59, v59
	v_exp_f32_e32 v60, v60
	v_exp_f32_e32 v61, v61
	v_exp_f32_e32 v62, v62
	v_exp_f32_e32 v63, v63
	v_cvt_pk_bf16_f32 v172, v56, v57
	v_cvt_pk_bf16_f32 v173, v58, v59
	v_cvt_pk_bf16_f32 v174, v60, v61
	v_cvt_pk_bf16_f32 v175, v62, v63
	v_pk_add_f32 v[32:33], v[32:33], v[170:171] op_sel:[0,1] op_sel_hi:[1,1] neg_lo:[0,1] neg_hi:[0,1]
	s_waitcnt lgkmcnt(0)
	v_mfma_f32_32x32x16_bf16 v[0:15], v[176:179], v[172:175], v[0:15]
	ds_read2_b64 v[176:179], v185 offset0:8 offset1:10
	v_pk_add_f32 v[34:35], v[34:35], v[170:171] op_sel:[0,1] op_sel_hi:[1,1] neg_lo:[0,1] neg_hi:[0,1]
	v_pk_add_f32 v[36:37], v[36:37], v[170:171] op_sel:[0,1] op_sel_hi:[1,1] neg_lo:[0,1] neg_hi:[0,1]
	v_pk_add_f32 v[38:39], v[38:39], v[170:171] op_sel:[0,1] op_sel_hi:[1,1] neg_lo:[0,1] neg_hi:[0,1]
	v_mfma_f32_32x32x16_bf16 v[16:31], v[180:183], v[172:175], v[16:31]
	v_exp_f32_e32 v32, v32
	v_exp_f32_e32 v33, v33
	v_exp_f32_e32 v34, v34
	v_exp_f32_e32 v35, v35
	v_exp_f32_e32 v36, v36
	v_exp_f32_e32 v37, v37
	v_exp_f32_e32 v38, v38
	v_exp_f32_e32 v39, v39
	v_cvt_pk_bf16_f32 v172, v32, v33
	v_cvt_pk_bf16_f32 v173, v34, v35
	v_cvt_pk_bf16_f32 v174, v36, v37
	v_cvt_pk_bf16_f32 v175, v38, v39
	v_pk_add_f32 v[40:41], v[40:41], v[170:171] op_sel:[0,1] op_sel_hi:[1,1] neg_lo:[0,1] neg_hi:[0,1]
	s_waitcnt lgkmcnt(0)
	v_mfma_f32_32x32x16_bf16 v[16:31], v[176:179], v[172:175], v[16:31]
	ds_read2_b64 v[176:179], v184 offset0:72 offset1:74
	v_pk_add_f32 v[42:43], v[42:43], v[170:171] op_sel:[0,1] op_sel_hi:[1,1] neg_lo:[0,1] neg_hi:[0,1]
	v_pk_add_f32 v[44:45], v[44:45], v[170:171] op_sel:[0,1] op_sel_hi:[1,1] neg_lo:[0,1] neg_hi:[0,1]
	v_pk_add_f32 v[46:47], v[46:47], v[170:171] op_sel:[0,1] op_sel_hi:[1,1] neg_lo:[0,1] neg_hi:[0,1]
	s_waitcnt lgkmcnt(0)
	v_mfma_f32_32x32x16_bf16 v[0:15], v[176:179], v[172:175], v[0:15]
	ds_read2_b64 v[176:179], v185 offset0:12 offset1:14
	v_exp_f32_e32 v40, v40
	v_exp_f32_e32 v41, v41
	v_exp_f32_e32 v42, v42
	v_exp_f32_e32 v43, v43
	v_exp_f32_e32 v44, v44
	v_exp_f32_e32 v45, v45
	v_exp_f32_e32 v46, v46
	v_exp_f32_e32 v47, v47
	v_cvt_pk_bf16_f32 v172, v40, v41
	v_cvt_pk_bf16_f32 v173, v42, v43
	v_cvt_pk_bf16_f32 v174, v44, v45
	v_cvt_pk_bf16_f32 v175, v46, v47
	s_waitcnt lgkmcnt(0)
	s_nop 0
	v_mfma_f32_32x32x16_bf16 v[16:31], v[176:179], v[172:175], v[16:31]
	ds_read2_b64 v[176:179], v184 offset0:76 offset1:78
	s_waitcnt lgkmcnt(0)
	v_mfma_f32_32x32x16_bf16 v[0:15], v[176:179], v[172:175], v[0:15]
	s_cbranch_vccnz .LBB0_1186
	s_xor_b32 s0, s18, 1
	s_mul_i32 s1, s0, 0x3400
	s_add_i32 s1, s1, 0
	v_add3_u32 v172, s1, v153, v154
	s_waitcnt vmcnt(4)
	ds_write_b128 v172, v[88:91]
	v_add3_u32 v172, s1, v155, v156
	s_waitcnt vmcnt(3)
	ds_write_b128 v172, v[92:95]
	v_add3_u32 v172, s1, v157, v158
	s_mulk_i32 s0, 0x2400
	s_waitcnt vmcnt(2)
	ds_write_b128 v172, v[98:101]
	v_add_u32_e32 v172, s0, v159
	v_lshl_add_u32 v173, v115, 1, v172
	v_lshl_add_u32 v172, v131, 1, v172
	s_waitcnt vmcnt(1)
	ds_write_b16 v173, v102 offset:26624
	ds_write_b16_d16_hi v173, v102 offset:26768
	ds_write_b16 v173, v103 offset:26912
	ds_write_b16_d16_hi v173, v103 offset:27056
	ds_write_b16 v173, v104 offset:27200
	ds_write_b16_d16_hi v173, v104 offset:27344
	ds_write_b16 v173, v105 offset:27488
	ds_write_b16_d16_hi v173, v105 offset:27632
	s_waitcnt vmcnt(0)
	ds_write_b16 v172, v106 offset:26624
	ds_write_b16_d16_hi v172, v106 offset:26768
	ds_write_b16 v172, v107 offset:26912
	ds_write_b16_d16_hi v172, v107 offset:27056
	ds_write_b16 v172, v108 offset:27200
	ds_write_b16_d16_hi v172, v108 offset:27344
	ds_write_b16 v172, v109 offset:27488
	ds_write_b16_d16_hi v172, v109 offset:27632
.LBB0_1186:
	v_pk_add_f32 v[48:49], v[48:49], v[50:51]
	v_pk_add_f32 v[52:53], v[52:53], v[54:55]
	v_pk_add_f32 v[56:57], v[56:57], v[58:59]
	v_pk_add_f32 v[60:61], v[60:61], v[62:63]
	v_pk_add_f32 v[32:33], v[32:33], v[34:35]
	v_pk_add_f32 v[36:37], v[36:37], v[38:39]
	v_pk_add_f32 v[40:41], v[40:41], v[42:43]
	v_pk_add_f32 v[44:45], v[44:45], v[46:47]
	v_pk_add_f32 v[48:49], v[48:49], v[52:53]
	v_pk_add_f32 v[56:57], v[56:57], v[60:61]
	v_pk_add_f32 v[32:33], v[32:33], v[36:37]
	v_pk_add_f32 v[40:41], v[40:41], v[44:45]
	v_pk_add_f32 v[48:49], v[48:49], v[56:57]
	v_pk_add_f32 v[32:33], v[32:33], v[40:41]
	v_pk_add_f32 v[32:33], v[32:33], v[48:49]
	s_nop 0
	v_add_f32_e32 v32, v32, v33
	s_add_i32 s16, s16, 64
	s_add_i32 s17, s17, 1
	v_fmac_f32_e32 v32, v170, v130
	s_cmpk_lg_i32 s16, 0x100
	s_waitcnt lgkmcnt(0)
	s_barrier
	s_cbranch_scc0 .LBB0_1188
	v_mov_b32_e32 v170, v32
	v_mov_b32_e32 v130, v171
	s_cmp_lt_u32 s17, 3
	s_cselect_b64 s[0:1], -1, 0
	s_cmp_gt_u32 s17, 2
	s_cbranch_scc0 .LBB0_1183
	s_branch .LBB0_1184

; template <int DQK, bool SWA> ...
;     ...
;     float mx = -INFINITY;
; #pragma unroll
;     for (int mt = 0; mt < 2; ++mt)
; #pragma unroll
;       for (int i = 0; i < 16; ++i) mx = fmaxf(mx, s[mt][i]);
;     mx = fmaxf(mx, __shfl_xor(mx, 32));
;     const float mnew = fmaxf(m, mx);
;     const float alpha = __builtin_amdgcn_exp2f(m - mnew);
;     m = mnew;
;     float psum = 0.f;
; #pragma unroll
;     for (int mt = 0; mt < 2; ++mt)
; #pragma unroll
;       for (int i = 0; i < 16; ++i) {
;         const float pv = __builtin_amdgcn_exp2f(s[mt][i] - mnew);
;         s[mt][i] = pv;
;         psum += pv;
;       }
;     lsum = lsum * alpha + psum;
; #pragma unroll
;     for (int a = 0; a < 2; ++a)
; #pragma unroll
.LBB0_1192:
	s_and_b32 s18, s15, 1
	s_mul_i32 s19, s18, 0x3400
	v_add3_u32 v169, v163, s19, v166
	ds_read_b128 v[224:227], v169
	ds_read_b128 v[228:231], v169 offset:32
	ds_read_b128 v[232:235], v169 offset:64
	ds_read_b128 v[236:239], v169 offset:96
	ds_read_b128 v[240:243], v169 offset:128
	ds_read_b128 v[244:247], v169 offset:160
	ds_read_b128 v[248:251], v169 offset:6656
	ds_read_b128 v[252:255], v169 offset:6688
	s_mul_i32 s19, s18, 0x2400
	v_add3_u32 v182, v165, s19, v167
	v_add_u32_e32 v183, 0x6800, v182
	v_add_u32_e32 v182, 0x7800, v182
	s_andn2_b64 vcc, exec, s[0:1]
	s_waitcnt lgkmcnt(7)
	v_mfma_f32_32x32x16_bf16 v[48:63], v[224:227], v[64:67], 0
	ds_read_b128 v[224:227], v169 offset:6720
	s_waitcnt lgkmcnt(7)
	v_mfma_f32_32x32x16_bf16 v[48:63], v[228:231], v[68:71], v[48:63]
	ds_read_b128 v[228:231], v169 offset:6752
	s_waitcnt lgkmcnt(7)
	v_mfma_f32_32x32x16_bf16 v[48:63], v[232:235], v[72:75], v[48:63]
	ds_read_b128 v[232:235], v169 offset:6784
	s_waitcnt lgkmcnt(7)
	v_mfma_f32_32x32x16_bf16 v[48:63], v[236:239], v[76:79], v[48:63]
	ds_read_b128 v[236:239], v169 offset:6816
	s_waitcnt lgkmcnt(7)
	v_mfma_f32_32x32x16_bf16 v[48:63], v[240:243], v[80:83], v[48:63]
	s_waitcnt lgkmcnt(6)
	v_mfma_f32_32x32x16_bf16 v[48:63], v[244:247], v[84:87], v[48:63]
	s_waitcnt lgkmcnt(5)
	v_mfma_f32_32x32x16_bf16 v[32:47], v[248:251], v[64:67], 0
	s_waitcnt lgkmcnt(4)
	v_mfma_f32_32x32x16_bf16 v[32:47], v[252:255], v[68:71], v[32:47]
	s_waitcnt lgkmcnt(3)
	v_mfma_f32_32x32x16_bf16 v[32:47], v[224:227], v[72:75], v[32:47]
	v_max3_f32 v169, v48, s22, v49
	v_max3_f32 v169, v169, v50, v51
	s_waitcnt lgkmcnt(2)
	v_mfma_f32_32x32x16_bf16 v[32:47], v[228:231], v[76:79], v[32:47]
	v_max3_f32 v169, v169, v52, v53
	v_max3_f32 v169, v169, v54, v55
	s_waitcnt lgkmcnt(1)
	v_mfma_f32_32x32x16_bf16 v[32:47], v[232:235], v[80:83], v[32:47]
	v_max3_f32 v169, v169, v56, v57
	v_max3_f32 v169, v169, v58, v59
	s_waitcnt lgkmcnt(0)
	v_mfma_f32_32x32x16_bf16 v[32:47], v[236:239], v[84:87], v[32:47]
	v_max3_f32 v169, v169, v60, v61
	v_max3_f32 v169, v169, v62, v63
	ds_read2_b64 v[174:177], v183 offset1:2
	ds_read2_b64 v[178:181], v183 offset0:4 offset1:6
	s_nop 7
	v_max3_f32 v169, v169, v32, v33
	v_max3_f32 v169, v169, v34, v35
	v_max3_f32 v169, v169, v36, v37
	v_max3_f32 v169, v169, v38, v39
	v_max3_f32 v169, v169, v40, v41
	v_max3_f32 v169, v169, v42, v43
	v_max3_f32 v169, v169, v44, v45
	v_max3_f32 v169, v169, v46, v47
	v_mov_b32_e32 v170, v169
	s_nop 1
	v_permlane32_swap_b32 v170, v169
	s_waitcnt lgkmcnt(0)
	v_max3_f32 v169, v130, v169, v170
	v_sub_f32_e32 v130, v130, v169
	v_pk_add_f32 v[48:49], v[48:49], v[168:169] op_sel:[0,1] op_sel_hi:[1,1] neg_lo:[0,1] neg_hi:[0,1]
	v_pk_add_f32 v[50:51], v[50:51], v[168:169] op_sel:[0,1] op_sel_hi:[1,1] neg_lo:[0,1] neg_hi:[0,1]
	v_pk_add_f32 v[52:53], v[52:53], v[168:169] op_sel:[0,1] op_sel_hi:[1,1] neg_lo:[0,1] neg_hi:[0,1]
	v_pk_add_f32 v[54:55], v[54:55], v[168:169] op_sel:[0,1] op_sel_hi:[1,1] neg_lo:[0,1] neg_hi:[0,1]
	v_exp_f32_e32 v130, v130
	v_exp_f32_e32 v48, v48
	v_exp_f32_e32 v49, v49
	v_exp_f32_e32 v50, v50
	v_exp_f32_e32 v51, v51
	v_exp_f32_e32 v52, v52
	v_exp_f32_e32 v53, v53
	v_exp_f32_e32 v54, v54
	v_exp_f32_e32 v55, v55
	v_pk_mul_f32 v[30:31], v[30:31], v[130:131] op_sel_hi:[1,0]
	v_pk_mul_f32 v[28:29], v[28:29], v[130:131] op_sel_hi:[1,0]
	v_pk_mul_f32 v[26:27], v[26:27], v[130:131] op_sel_hi:[1,0]
	v_pk_mul_f32 v[24:25], v[24:25], v[130:131] op_sel_hi:[1,0]
	v_pk_mul_f32 v[22:23], v[22:23], v[130:131] op_sel_hi:[1,0]
	v_pk_mul_f32 v[20:21], v[20:21], v[130:131] op_sel_hi:[1,0]
	v_pk_mul_f32 v[18:19], v[18:19], v[130:131] op_sel_hi:[1,0]
	v_pk_mul_f32 v[16:17], v[16:17], v[130:131] op_sel_hi:[1,0]
	v_cvt_pk_bf16_f32 v170, v48, v49
	v_cvt_pk_bf16_f32 v171, v50, v51
	v_cvt_pk_bf16_f32 v172, v52, v53
	v_cvt_pk_bf16_f32 v173, v54, v55
	v_pk_mul_f32 v[14:15], v[14:15], v[130:131] op_sel_hi:[1,0]
	v_pk_mul_f32 v[12:13], v[12:13], v[130:131] op_sel_hi:[1,0]
	v_mfma_f32_32x32x16_bf16 v[16:31], v[174:177], v[170:173], v[16:31]
	ds_read2_b64 v[174:177], v182 offset0:64 offset1:66
	v_mul_f32_e64 v10, v10, v130
	v_mul_f32_e64 v11, v11, v130
	v_mul_f32_e64 v8, v8, v130
	v_mul_f32_e64 v9, v9, v130
	v_pk_mul_f32 v[6:7], v[6:7], v[130:131] op_sel_hi:[1,0]
	v_pk_mul_f32 v[4:5], v[4:5], v[130:131] op_sel_hi:[1,0]
	v_pk_mul_f32 v[2:3], v[2:3], v[130:131] op_sel_hi:[1,0]
	v_pk_mul_f32 v[0:1], v[0:1], v[130:131] op_sel_hi:[1,0]
	v_pk_add_f32 v[56:57], v[56:57], v[168:169] op_sel:[0,1] op_sel_hi:[1,1] neg_lo:[0,1] neg_hi:[0,1]
	s_waitcnt lgkmcnt(0)
; #define MFMA(a, b, c) __builtin_amdgcn_mfma_f32_32x32x16_bf16((a), (b), (c), 0, 0, 0)
; template <int DQK, bool SWA> ...
;     ...
; #pragma unroll
;     for (int mt = 0; mt < 2; ++mt)
; #pragma unroll
;       for (int i = 0; i < 16; ++i) {
;         const float pv = __builtin_amdgcn_exp2f(s[mt][i] - mnew);
;         s[mt][i] = pv;
;         psum += pv;
;       }
;     lsum = lsum * alpha + psum;
; #pragma unroll
;     for (int a = 0; a < 2; ++a)
; #pragma unroll
;       for (int i = 0; i < 16; ++i) o[a][i] *= alpha;
; #pragma unroll
;     for (int mt = 0; mt < 2; ++mt)
; #pragma unroll
;       for (int sx = 0; sx < 2; ++sx) {
;         uint4 pu;
;         pu.x = pack2(s[mt][8 * sx + 0], s[mt][8 * sx + 1]);
;         pu.y = pack2(s[mt][8 * sx + 2], s[mt][8 * sx + 3]);
;         pu.z = pack2(s[mt][8 * sx + 4], s[mt][8 * sx + 5]);
;         pu.w = pack2(s[mt][8 * sx + 6], s[mt][8 * sx + 7]);
;         const bf16x8 pfv = __builtin_bit_cast(bf16x8, pu);
; #pragma unroll
;         for (int dt = 0; dt < 2; ++dt) {
;           const u16* vp = Vt + buf * 64 * VSTR + (dt * 32 + r) * VSTR + mt * 32 + 16 * sx + 4 * hh;
;           const uint2 v0 = *(const uint2*)(vp);
;           const uint2 v1 = *(const uint2*)(vp + 8);
;           const uint4 vu = make_uint4(v0.x, v0.y, v1.x, v1.y);
;           o[dt] = MFMA(__builtin_bit_cast(bf16x8, vu), pfv, o[dt]);
;         }
;       }
;     if (it + 1 < nt) A_STORES(buf ^ 1);
;     __syncthreads();
	v_mfma_f32_32x32x16_bf16 v[0:15], v[174:177], v[170:173], v[0:15]
	ds_read2_b64 v[174:177], v182 offset0:68 offset1:70
	v_pk_add_f32 v[58:59], v[58:59], v[168:169] op_sel:[0,1] op_sel_hi:[1,1] neg_lo:[0,1] neg_hi:[0,1]
	v_pk_add_f32 v[60:61], v[60:61], v[168:169] op_sel:[0,1] op_sel_hi:[1,1] neg_lo:[0,1] neg_hi:[0,1]
	v_pk_add_f32 v[62:63], v[62:63], v[168:169] op_sel:[0,1] op_sel_hi:[1,1] neg_lo:[0,1] neg_hi:[0,1]
	v_exp_f32_e32 v56, v56
	v_exp_f32_e32 v57, v57
	v_exp_f32_e32 v58, v58
	v_exp_f32_e32 v59, v59
	v_exp_f32_e32 v60, v60
	v_exp_f32_e32 v61, v61
	v_exp_f32_e32 v62, v62
	v_exp_f32_e32 v63, v63
	v_cvt_pk_bf16_f32 v170, v56, v57
	v_cvt_pk_bf16_f32 v171, v58, v59
	v_cvt_pk_bf16_f32 v172, v60, v61
	v_cvt_pk_bf16_f32 v173, v62, v63
	v_pk_add_f32 v[32:33], v[32:33], v[168:169] op_sel:[0,1] op_sel_hi:[1,1] neg_lo:[0,1] neg_hi:[0,1]
	s_waitcnt lgkmcnt(0)
	v_mfma_f32_32x32x16_bf16 v[0:15], v[174:177], v[170:173], v[0:15]
	ds_read2_b64 v[174:177], v183 offset0:8 offset1:10
	v_pk_add_f32 v[34:35], v[34:35], v[168:169] op_sel:[0,1] op_sel_hi:[1,1] neg_lo:[0,1] neg_hi:[0,1]
	v_pk_add_f32 v[36:37], v[36:37], v[168:169] op_sel:[0,1] op_sel_hi:[1,1] neg_lo:[0,1] neg_hi:[0,1]
	v_pk_add_f32 v[38:39], v[38:39], v[168:169] op_sel:[0,1] op_sel_hi:[1,1] neg_lo:[0,1] neg_hi:[0,1]
	v_mfma_f32_32x32x16_bf16 v[16:31], v[178:181], v[170:173], v[16:31]
	v_exp_f32_e32 v32, v32
	v_exp_f32_e32 v33, v33
	v_exp_f32_e32 v34, v34
	v_exp_f32_e32 v35, v35
	v_exp_f32_e32 v36, v36
	v_exp_f32_e32 v37, v37
	v_exp_f32_e32 v38, v38
	v_exp_f32_e32 v39, v39
	v_cvt_pk_bf16_f32 v170, v32, v33
	v_cvt_pk_bf16_f32 v171, v34, v35
	v_cvt_pk_bf16_f32 v172, v36, v37
	v_cvt_pk_bf16_f32 v173, v38, v39
	v_pk_add_f32 v[40:41], v[40:41], v[168:169] op_sel:[0,1] op_sel_hi:[1,1] neg_lo:[0,1] neg_hi:[0,1]
	s_waitcnt lgkmcnt(0)
	v_mfma_f32_32x32x16_bf16 v[16:31], v[174:177], v[170:173], v[16:31]
	ds_read2_b64 v[174:177], v182 offset0:72 offset1:74
	v_pk_add_f32 v[42:43], v[42:43], v[168:169] op_sel:[0,1] op_sel_hi:[1,1] neg_lo:[0,1] neg_hi:[0,1]
	v_pk_add_f32 v[44:45], v[44:45], v[168:169] op_sel:[0,1] op_sel_hi:[1,1] neg_lo:[0,1] neg_hi:[0,1]
	v_pk_add_f32 v[46:47], v[46:47], v[168:169] op_sel:[0,1] op_sel_hi:[1,1] neg_lo:[0,1] neg_hi:[0,1]
	s_waitcnt lgkmcnt(0)
	v_mfma_f32_32x32x16_bf16 v[0:15], v[174:177], v[170:173], v[0:15]
	ds_read2_b64 v[174:177], v183 offset0:12 offset1:14
	v_exp_f32_e32 v40, v40
	v_exp_f32_e32 v41, v41
	v_exp_f32_e32 v42, v42
	v_exp_f32_e32 v43, v43
	v_exp_f32_e32 v44, v44
	v_exp_f32_e32 v45, v45
	v_exp_f32_e32 v46, v46
	v_exp_f32_e32 v47, v47
	v_cvt_pk_bf16_f32 v170, v40, v41
	v_cvt_pk_bf16_f32 v171, v42, v43
	v_cvt_pk_bf16_f32 v172, v44, v45
	v_cvt_pk_bf16_f32 v173, v46, v47
	s_waitcnt lgkmcnt(0)
	s_nop 0
	v_mfma_f32_32x32x16_bf16 v[16:31], v[174:177], v[170:173], v[16:31]
	ds_read2_b64 v[174:177], v182 offset0:76 offset1:78
	s_waitcnt lgkmcnt(0)
	v_mfma_f32_32x32x16_bf16 v[0:15], v[174:177], v[170:173], v[0:15]
	s_cbranch_vccnz .LBB0_1194
	s_xor_b32 s0, s18, 1
	s_mul_i32 s1, s0, 0x3400
	s_add_i32 s1, s1, 0
	v_add3_u32 v170, s1, v156, v157
	s_waitcnt vmcnt(4)
	ds_write_b128 v170, v[88:91]
	v_add3_u32 v170, s1, v158, v159
	s_waitcnt vmcnt(3)
	ds_write_b128 v170, v[92:95]
	v_add3_u32 v170, s1, v160, v161
	s_mulk_i32 s0, 0x2400
	s_waitcnt vmcnt(2)
	ds_write_b128 v170, v[98:101]
	v_add_u32_e32 v170, s0, v162
	v_lshl_add_u32 v171, v154, 1, v170
	v_lshl_add_u32 v170, v155, 1, v170
	s_waitcnt vmcnt(1)
	ds_write_b16 v171, v102 offset:26624
	ds_write_b16_d16_hi v171, v102 offset:26768
	ds_write_b16 v171, v103 offset:26912
	ds_write_b16_d16_hi v171, v103 offset:27056
	ds_write_b16 v171, v104 offset:27200
	ds_write_b16_d16_hi v171, v104 offset:27344
	ds_write_b16 v171, v105 offset:27488
	ds_write_b16_d16_hi v171, v105 offset:27632
	s_waitcnt vmcnt(0)
	ds_write_b16 v170, v106 offset:26624
	ds_write_b16_d16_hi v170, v106 offset:26768
	ds_write_b16 v170, v107 offset:26912
	ds_write_b16_d16_hi v170, v107 offset:27056
	ds_write_b16 v170, v108 offset:27200
	ds_write_b16_d16_hi v170, v108 offset:27344
	ds_write_b16 v170, v109 offset:27488
	ds_write_b16_d16_hi v170, v109 offset:27632
.LBB0_1194:
	v_pk_add_f32 v[48:49], v[48:49], v[50:51]
	v_pk_add_f32 v[52:53], v[52:53], v[54:55]
	v_pk_add_f32 v[56:57], v[56:57], v[58:59]
	v_pk_add_f32 v[60:61], v[60:61], v[62:63]
	v_pk_add_f32 v[32:33], v[32:33], v[34:35]
	v_pk_add_f32 v[36:37], v[36:37], v[38:39]
	v_pk_add_f32 v[40:41], v[40:41], v[42:43]
	v_pk_add_f32 v[44:45], v[44:45], v[46:47]
	v_pk_add_f32 v[48:49], v[48:49], v[52:53]
	v_pk_add_f32 v[56:57], v[56:57], v[60:61]
	v_pk_add_f32 v[32:33], v[32:33], v[36:37]
	v_pk_add_f32 v[40:41], v[40:41], v[44:45]
	v_pk_add_f32 v[48:49], v[48:49], v[56:57]
	v_pk_add_f32 v[32:33], v[32:33], v[40:41]
	v_pk_add_f32 v[32:33], v[32:33], v[48:49]
	s_nop 0
	v_add_f32_e32 v32, v32, v33
	s_add_i32 s15, s15, 1
	s_add_i32 s16, s16, 64
	s_add_i32 s17, s17, 64
	v_fmac_f32_e32 v32, v168, v130
	s_cmp_lg_u32 s15, 36
	s_waitcnt lgkmcnt(0)
	s_barrier
	s_cbranch_scc0 .LBB0_1179
	v_mov_b32_e32 v168, v32
	v_mov_b32_e32 v130, v169
	s_cmp_lt_u32 s15, 35
	s_cselect_b64 s[0:1], -1, 0
	s_cmp_gt_u32 s15, 34
	s_cbranch_scc0 .LBB0_1191
	s_branch .LBB0_1192
